# sg item ks loop: unrolled 8x with all spatial-weight row loads issued upfront (counted waits)
# speedup vs baseline: 1.1706x; 1.0012x over previous
; DI int TID() { int t = threadIdx.x; asm volatile("" : "+v"(t)); return t; }
; DI void sg_item(const Params& p, int l, int item, char* lds, int dry) {
;   const int g = item & 7, chunk = (item >> 3) & 31, b = item >> 8;
;   u16* vn = (u16*)lds;
;   const int tid = TID(), lane = tid & 63, w = tid >> 6, r = lane & 31, h = lane >> 5;
;   const size_t tokbase = (size_t)b * S_ + chunk * 128;
; #pragma unroll
;   for (int i = 0; i < 4; ++i) {
;     const int id = tid + 256 * i, row = id >> 3, c = id & 7;
;     *(uint4*)(vn + row * 72 + c * 8) = *(const uint4*)(p.z + (tokbase + row) * ZS + VD + g * 64 + c * 8);
;   }
;   __syncthreads();
;   const int t = 32 * w + r;
;   const float* wr = p.w_spatial + (((size_t)(l * 8 + g) * 128) + t) * 128;
;   const int q4 = (lane & 15) >> 2, p4 = lane & 3, blk = (lane >> 4) & 1;
;   f32x16 acc[2];
; #pragma unroll
;   for (int i = 0; i < 16; ++i) { acc[0][i] = 0.f; acc[1][i] = 0.f; }
;   const int nks = 2 * (w + 1);
;   for (int ks = 0; ks < nks; ++ks) {
;     const int s0 = ks * 16 + 8 * h;
;     const float4 w0 = *(const float4*)(wr + s0);
.LBB0_778:
	s_or_b64 exec, exec, s[0:1]
	s_waitcnt lgkmcnt(0)
	s_barrier
	ds_read_b32 v0, v221
	s_movk_i32 s0, 0xbff
	s_waitcnt lgkmcnt(0)
	v_cmp_lt_i32_e32 vcc, s0, v0
	v_readfirstlane_b32 s5, v0
	s_mov_b64 s[0:1], -1
	s_cbranch_vccnz .LBB0_773
	s_and_b32 s4, s5, 7
	s_lshl_b32 s6, s4, 6
	s_cmpk_gt_i32 s5, 0x7ff
	s_cbranch_scc0 .LBB0_913
	v_mov_b32_e32 v38, v209
	s_lshl_b32 s0, s5, 4
	v_readlane_b32 s80, v253, 12
	s_and_b32 s7, s0, 0x3f80
	v_ashrrev_i32_e32 v4, 3, v38
	v_readlane_b32 s86, v253, 18
	v_readlane_b32 s87, v253, 19
	v_add_u32_e32 v2, s7, v4
	v_lshlrev_b32_e32 v0, 4, v38
	v_mov_b64_e32 v[6:7], s[86:87]
	v_mad_i64_i32 v[2:3], s[0:1], v2, s75, v[6:7]
	s_lshl_b32 s18, s6, 1
	v_and_b32_e32 v0, 0x70, v0
	v_lshl_add_u64 v[2:3], v[2:3], 0, s[18:19]
	v_lshl_add_u64 v[2:3], v[2:3], 0, v[0:1]
	s_movk_i32 s2, 0x2000
	v_add_co_u32_e32 v2, vcc, s2, v2
	v_mad_u64_u32 v[8:9], s[0:1], v4, s76, v[0:1]
	s_nop 0
	v_addc_co_u32_e32 v3, vcc, 0, v3, vcc
	global_load_dwordx4 v[2:5], v[2:3], off offset:2560
	v_ashrrev_i32_e32 v34, 6, v38
	v_and_b32_e32 v39, 31, v38
	v_lshlrev_b32_e32 v40, 5, v34
	v_bfe_u32 v37, v38, 5, 1
	v_mov_b32_e32 v33, 0
	s_movk_i32 s96, 0x2000
	s_waitcnt vmcnt(32)
	v_or_b32_e32 v36, v40, v39
	s_lshl_b32 s9, s4, 7
	v_mov_b32_e32 v32, v33
	v_mov_b32_e32 v31, v33
	v_mov_b32_e32 v30, v33
	v_mov_b32_e32 v29, v33
	v_mov_b32_e32 v28, v33
	v_mov_b32_e32 v27, v33
	v_mov_b32_e32 v26, v33
	v_mov_b32_e32 v25, v33
	v_mov_b32_e32 v24, v33
	v_mov_b32_e32 v23, v33
	v_mov_b32_e32 v22, v33
	v_mov_b32_e32 v21, v33
	v_mov_b32_e32 v20, v33
	v_mov_b32_e32 v19, v33
	v_mov_b32_e32 v18, v33
	v_mov_b32_e32 v17, v33
	v_mov_b32_e32 v16, v33
	v_mov_b32_e32 v15, v33
	v_mov_b32_e32 v14, v33
	v_mov_b32_e32 v13, v33
	v_mov_b32_e32 v12, v33
	v_mov_b32_e32 v11, v33
	v_mov_b32_e32 v10, v33
	v_readlane_b32 s81, v253, 13
	v_readlane_b32 s82, v253, 14
	v_readlane_b32 s83, v253, 15
	v_readlane_b32 s84, v253, 16
	v_readlane_b32 s85, v253, 17
	v_readlane_b32 s88, v253, 20
	v_readlane_b32 s89, v253, 21
	v_readlane_b32 s90, v253, 22
	v_readlane_b32 s91, v253, 23
	v_readlane_b32 s92, v253, 24
	v_readlane_b32 s93, v253, 25
	v_readlane_b32 s94, v253, 26
	v_readlane_b32 s95, v253, 27
	s_waitcnt vmcnt(0)
	ds_write_b128 v8, v[2:5]
	v_add_u32_e32 v2, 0x100, v38
	v_ashrrev_i32_e32 v4, 3, v2
	v_add_u32_e32 v2, s7, v4
	v_mad_i64_i32 v[2:3], s[0:1], v2, s75, v[6:7]
	v_lshl_add_u64 v[2:3], v[2:3], 0, s[18:19]
	v_lshl_add_u64 v[2:3], v[2:3], 0, v[0:1]
	v_add_co_u32_e32 v2, vcc, s2, v2
	v_mad_u64_u32 v[8:9], s[0:1], v4, s76, v[0:1]
	s_nop 0
	v_addc_co_u32_e32 v3, vcc, 0, v3, vcc
	global_load_dwordx4 v[2:5], v[2:3], off offset:2560
	s_waitcnt vmcnt(0)
	ds_write_b128 v8, v[2:5]
	v_add_u32_e32 v2, 0x200, v38
	v_ashrrev_i32_e32 v4, 3, v2
	v_add_u32_e32 v2, s7, v4
	v_mad_i64_i32 v[2:3], s[0:1], v2, s75, v[6:7]
	v_lshl_add_u64 v[2:3], v[2:3], 0, s[18:19]
	v_lshl_add_u64 v[2:3], v[2:3], 0, v[0:1]
	v_add_co_u32_e32 v2, vcc, s2, v2
	v_mad_u64_u32 v[8:9], s[0:1], v4, s76, v[0:1]
	s_nop 0
	v_addc_co_u32_e32 v3, vcc, 0, v3, vcc
	global_load_dwordx4 v[2:5], v[2:3], off offset:2560
	v_mov_b32_e32 v9, v33
	s_waitcnt vmcnt(0)
	ds_write_b128 v8, v[2:5]
	v_add_u32_e32 v2, 0x300, v38
	v_ashrrev_i32_e32 v4, 3, v2
	v_add_u32_e32 v2, s7, v4
	v_mad_i64_i32 v[2:3], s[0:1], v2, s75, v[6:7]
	v_lshl_add_u64 v[2:3], v[2:3], 0, s[18:19]
	v_lshl_add_u64 v[2:3], v[2:3], 0, v[0:1]
	v_add_co_u32_e32 v2, vcc, s2, v2
	v_mad_u64_u32 v[6:7], s[0:1], v4, s76, v[0:1]
	s_nop 0
	v_addc_co_u32_e32 v3, vcc, 0, v3, vcc
	global_load_dwordx4 v[2:5], v[2:3], off offset:2560
	v_cmp_lt_i32_e32 vcc, -1, v34
	v_lshlrev_b32_e32 v0, 3, v37
	v_mov_b32_e32 v8, v33
	v_mov_b32_e32 v7, v33
	s_waitcnt vmcnt(0)
	ds_write_b128 v6, v[2:5]
	v_mov_b32_e32 v6, v33
	v_mov_b32_e32 v5, v33
	v_mov_b32_e32 v4, v33
	v_mov_b32_e32 v3, v33
	v_mov_b32_e32 v2, v33
	s_waitcnt lgkmcnt(0)
	s_barrier
	s_and_saveexec_b64 s[0:1], vcc
	s_cbranch_execz .LBB0_784
	v_bfe_u32 v2, v38, 2, 2
	v_lshlrev_b32_e32 v4, 1, v38
	v_mul_u32_u24_e32 v3, 0x480, v37
	v_mul_u32_u24_e32 v2, 0x90, v2
	v_and_b32_e32 v4, 32, v4
	v_add3_u32 v2, v3, v2, v4
	v_and_b32_e32 v3, 3, v38
	v_lshlrev_b32_e32 v3, 3, v3
	s_movk_i32 s2, 0x280
	v_add3_u32 v37, v2, v3, s2
	v_add_u32_e32 v2, v40, v39
	v_ashrrev_i32_e32 v3, 31, v2
	s_add_i32 s2, s8, s9
	s_mov_b32 s3, s19
	v_lshl_add_u64 v[2:3], v[2:3], 0, s[2:3]
	v_lshlrev_b64 v[2:3], 9, v[2:3]
	v_readlane_b32 s2, v253, 32
	v_and_or_b32 v2, v38, 32, v2
	v_readlane_b32 s3, v253, 33
	v_mov_b32_e32 v35, v36
	v_lshl_add_u32 v34, v34, 1, 2
	v_lshl_add_u64 v[38:39], s[2:3], 0, v[2:3]
	v_mov_b32_e32 v2, 0
	s_mov_b64 s[2:3], 0
	v_mov_b32_e32 v40, v0
	v_mov_b32_e32 v3, v2
	v_mov_b32_e32 v4, v2
	v_mov_b32_e32 v5, v2
	v_mov_b32_e32 v6, v2
	v_mov_b32_e32 v7, v2
	v_mov_b32_e32 v8, v2
	v_mov_b32_e32 v9, v2
	v_mov_b32_e32 v10, v2
	v_mov_b32_e32 v11, v2
	v_mov_b32_e32 v12, v2
	v_mov_b32_e32 v13, v2
	v_mov_b32_e32 v14, v2
	v_mov_b32_e32 v15, v2
	v_mov_b32_e32 v16, v2
	v_mov_b32_e32 v17, v2
	v_mov_b32_e32 v18, v2
	v_mov_b32_e32 v19, v2
	v_mov_b32_e32 v20, v2
	v_mov_b32_e32 v21, v2
	v_mov_b32_e32 v22, v2
	v_mov_b32_e32 v23, v2
	v_mov_b32_e32 v24, v2
	v_mov_b32_e32 v25, v2
	v_mov_b32_e32 v26, v2
	v_mov_b32_e32 v27, v2
	v_mov_b32_e32 v28, v2
	v_mov_b32_e32 v29, v2
	v_mov_b32_e32 v30, v2
	v_mov_b32_e32 v31, v2
	v_mov_b32_e32 v32, v2
	v_mov_b32_e32 v33, v2
	s_mov_b32 s10, 0x5040100
	global_load_dwordx4 v[96:99], v[38:39], off offset:-16
	global_load_dwordx4 v[100:103], v[38:39], off
	global_load_dwordx4 v[104:107], v[38:39], off offset:48
	global_load_dwordx4 v[108:111], v[38:39], off offset:64
	global_load_dwordx4 v[112:115], v[38:39], off offset:112
	global_load_dwordx4 v[116:119], v[38:39], off offset:128
	global_load_dwordx4 v[120:123], v[38:39], off offset:176
	global_load_dwordx4 v[124:127], v[38:39], off offset:192
	global_load_dwordx4 v[128:131], v[38:39], off offset:240
	global_load_dwordx4 v[132:135], v[38:39], off offset:256
	global_load_dwordx4 v[136:139], v[38:39], off offset:304
	global_load_dwordx4 v[140:143], v[38:39], off offset:320
	global_load_dwordx4 v[144:147], v[38:39], off offset:368
	global_load_dwordx4 v[148:151], v[38:39], off offset:384
	global_load_dwordx4 v[152:155], v[38:39], off offset:432
	global_load_dwordx4 v[156:159], v[38:39], off offset:448
; #define MFMA(a, b, c) __builtin_amdgcn_mfma_f32_32x32x16_f16(__builtin_bit_cast(h16x8, (a)), __builtin_bit_cast(h16x8, (b)), (c), 0, 0, 0)
; DI unsigned pk2(float a, float b) { f2_t v = {a, b}; bf2_t r = __builtin_convertvector(v, bf2_t); return __builtin_bit_cast(unsigned, r); }
; DI void sg_item(const Params& p, int l, int item, char* lds, int dry) {
;     ...
;   const int nks = 2 * (w + 1);
;   for (int ks = 0; ks < nks; ++ks) {
;     const int s0 = ks * 16 + 8 * h;
;     const float4 w0 = *(const float4*)(wr + s0);
;     const float4 w1 = *(const float4*)(wr + s0 + 4);
;     float wv[8] = {w0.x, w0.y, w0.z, w0.w, w1.x, w1.y, w1.z, w1.w};
; #pragma unroll
;     for (int j = 0; j < 8; ++j) wv[j] = (s0 + j <= t) ? wv[j] : 0.f;
;     const uint4 uu = make_uint4(pk2(wv[0], wv[1]), pk2(wv[2], wv[3]), pk2(wv[4], wv[5]), pk2(wv[6], wv[7]));
;     const bf16x8 bfr = __builtin_bit_cast(bf16x8, uu);
; #pragma unroll
;     for (int db = 0; db < 2; ++db) {
;       const u16* vp = vn + (ks * 16 + 8 * h + q4) * 72 + db * 32 + 16 * blk + 4 * p4;
;       const s16x4 lo = __builtin_amdgcn_ds_read_tr16_b64_v4i16((__attribute__((address_space(3))) s16x4*)(vp));
;       const s16x4 hi = __builtin_amdgcn_ds_read_tr16_b64_v4i16((__attribute__((address_space(3))) s16x4*)(vp + 4 * 72));
;       const bf16x8 afr = __builtin_shufflevector(lo, hi, 0, 1, 2, 3, 4, 5, 6, 7);
;       acc[db] = MFMA(afr, bfr, acc[db]);
;     }
;   }
.LBB0_782:
	v_cmp_gt_i32_e32 vcc, v36, v40
	v_or_b32_e32 v50, 2, v40
	v_or_b32_e32 v52, 4, v40
	v_or_b32_e32 v51, 5, v40
	v_or_b32_e32 v54, 6, v40
	v_or_b32_e32 v53, 7, v40
	v_add_u32_e32 v34, -1, v34
	v_lshl_add_u64 v[38:39], v[38:39], 0, 64
	s_waitcnt vmcnt(15)
	v_cndmask_b32_e32 v41, 0, v97, vcc
	v_cmp_le_i32_e32 vcc, v40, v36
	v_or_b32_e32 v43, 3, v40
	v_add_u32_e32 v40, 16, v40
	v_cndmask_b32_e32 v42, 0, v96, vcc
	v_cvt_pk_f16_f32 v42, v42, v41
	v_cvt_pk_f16_f32 v41, v98, v99
	v_cmp_le_i32_e32 vcc, v50, v36
	s_nop 1
	v_cndmask_b32_e32 v44, 0, v41, vcc
	v_cmp_le_i32_e32 vcc, v43, v35
	v_lshrrev_b32_e32 v41, 16, v41
	s_nop 0
	v_cndmask_b32_e32 v41, 0, v41, vcc
	v_perm_b32 v43, v41, v44, s10
	s_waitcnt vmcnt(14)
	v_cvt_pk_f16_f32 v41, v100, v101
	v_cmp_le_i32_e32 vcc, v52, v36
	s_nop 1
	v_cndmask_b32_e32 v44, 0, v41, vcc
	v_cmp_le_i32_e32 vcc, v51, v35
	v_lshrrev_b32_e32 v41, 16, v41
	s_nop 0
	v_cndmask_b32_e32 v41, 0, v41, vcc
	v_perm_b32 v44, v41, v44, s10
	v_cvt_pk_f16_f32 v41, v102, v103
	v_cmp_le_i32_e32 vcc, v54, v36
	s_nop 1
	v_cndmask_b32_e32 v45, 0, v41, vcc
	v_cmp_le_i32_e32 vcc, v53, v35
	v_lshrrev_b32_e32 v41, 16, v41
	s_nop 0
	v_cndmask_b32_e32 v41, 0, v41, vcc
	v_perm_b32 v45, v41, v45, s10
	v_add_u32_e32 v41, 0xfffffd80, v37
	ds_read_b64_tr_b16 v[46:47], v41
	v_subrev_u32_e32 v41, 64, v37
	ds_read_b64_tr_b16 v[48:49], v41
	v_add_u32_e32 v41, 0xfffffdc0, v37
	s_waitcnt lgkmcnt(0)
	v_mfma_f32_32x32x16_f16 v[18:33], v[46:49], v[42:45], v[18:33]
	ds_read_b64_tr_b16 v[46:47], v41
	ds_read_b64_tr_b16 v[48:49], v37
	v_cmp_eq_u32_e32 vcc, 0, v34
	v_add_u32_e32 v37, 0x900, v37
	s_or_b64 s[2:3], vcc, s[2:3]
	s_waitcnt lgkmcnt(0)
	v_mfma_f32_32x32x16_f16 v[2:17], v[46:49], v[42:45], v[2:17]
	s_andn2_b64 exec, exec, s[2:3]
	s_cbranch_execz .Lsg_ksdone
.Lsg_ks1:
	v_cmp_gt_i32_e32 vcc, v36, v40
	v_or_b32_e32 v50, 2, v40
	v_or_b32_e32 v52, 4, v40
	v_or_b32_e32 v51, 5, v40
	v_or_b32_e32 v54, 6, v40
	v_or_b32_e32 v53, 7, v40
	v_add_u32_e32 v34, -1, v34
	v_lshl_add_u64 v[38:39], v[38:39], 0, 64
	s_waitcnt vmcnt(13)
	v_cndmask_b32_e32 v41, 0, v105, vcc
	v_cmp_le_i32_e32 vcc, v40, v36
	v_or_b32_e32 v43, 3, v40
	v_add_u32_e32 v40, 16, v40
	v_cndmask_b32_e32 v42, 0, v104, vcc
	v_cvt_pk_f16_f32 v42, v42, v41
	v_cvt_pk_f16_f32 v41, v106, v107
	v_cmp_le_i32_e32 vcc, v50, v36
	s_nop 1
	v_cndmask_b32_e32 v44, 0, v41, vcc
	v_cmp_le_i32_e32 vcc, v43, v35
	v_lshrrev_b32_e32 v41, 16, v41
	s_nop 0
	v_cndmask_b32_e32 v41, 0, v41, vcc
	v_perm_b32 v43, v41, v44, s10
	s_waitcnt vmcnt(12)
	v_cvt_pk_f16_f32 v41, v108, v109
	v_cmp_le_i32_e32 vcc, v52, v36
	s_nop 1
	v_cndmask_b32_e32 v44, 0, v41, vcc
	v_cmp_le_i32_e32 vcc, v51, v35
	v_lshrrev_b32_e32 v41, 16, v41
	s_nop 0
	v_cndmask_b32_e32 v41, 0, v41, vcc
	v_perm_b32 v44, v41, v44, s10
	v_cvt_pk_f16_f32 v41, v110, v111
	v_cmp_le_i32_e32 vcc, v54, v36
	s_nop 1
	v_cndmask_b32_e32 v45, 0, v41, vcc
	v_cmp_le_i32_e32 vcc, v53, v35
	v_lshrrev_b32_e32 v41, 16, v41
	s_nop 0
	v_cndmask_b32_e32 v41, 0, v41, vcc
	v_perm_b32 v45, v41, v45, s10
	v_add_u32_e32 v41, 0xfffffd80, v37
	ds_read_b64_tr_b16 v[46:47], v41
	v_subrev_u32_e32 v41, 64, v37
	ds_read_b64_tr_b16 v[48:49], v41
	v_add_u32_e32 v41, 0xfffffdc0, v37
	s_waitcnt lgkmcnt(0)
	v_mfma_f32_32x32x16_f16 v[18:33], v[46:49], v[42:45], v[18:33]
	ds_read_b64_tr_b16 v[46:47], v41
	ds_read_b64_tr_b16 v[48:49], v37
	v_cmp_eq_u32_e32 vcc, 0, v34
	v_add_u32_e32 v37, 0x900, v37
	s_or_b64 s[2:3], vcc, s[2:3]
	s_waitcnt lgkmcnt(0)
	v_mfma_f32_32x32x16_f16 v[2:17], v[46:49], v[42:45], v[2:17]
	s_andn2_b64 exec, exec, s[2:3]
	s_cbranch_execz .Lsg_ksdone
.Lsg_ks2:
	v_cmp_gt_i32_e32 vcc, v36, v40
	v_or_b32_e32 v50, 2, v40
	v_or_b32_e32 v52, 4, v40
	v_or_b32_e32 v51, 5, v40
	v_or_b32_e32 v54, 6, v40
	v_or_b32_e32 v53, 7, v40
	v_add_u32_e32 v34, -1, v34
	v_lshl_add_u64 v[38:39], v[38:39], 0, 64
	s_waitcnt vmcnt(11)
	v_cndmask_b32_e32 v41, 0, v113, vcc
	v_cmp_le_i32_e32 vcc, v40, v36
	v_or_b32_e32 v43, 3, v40
	v_add_u32_e32 v40, 16, v40
	v_cndmask_b32_e32 v42, 0, v112, vcc
	v_cvt_pk_f16_f32 v42, v42, v41
	v_cvt_pk_f16_f32 v41, v114, v115
	v_cmp_le_i32_e32 vcc, v50, v36
	s_nop 1
	v_cndmask_b32_e32 v44, 0, v41, vcc
	v_cmp_le_i32_e32 vcc, v43, v35
	v_lshrrev_b32_e32 v41, 16, v41
	s_nop 0
	v_cndmask_b32_e32 v41, 0, v41, vcc
	v_perm_b32 v43, v41, v44, s10
	s_waitcnt vmcnt(10)
	v_cvt_pk_f16_f32 v41, v116, v117
	v_cmp_le_i32_e32 vcc, v52, v36
	s_nop 1
	v_cndmask_b32_e32 v44, 0, v41, vcc
	v_cmp_le_i32_e32 vcc, v51, v35
	v_lshrrev_b32_e32 v41, 16, v41
	s_nop 0
	v_cndmask_b32_e32 v41, 0, v41, vcc
	v_perm_b32 v44, v41, v44, s10
	v_cvt_pk_f16_f32 v41, v118, v119
	v_cmp_le_i32_e32 vcc, v54, v36
	s_nop 1
	v_cndmask_b32_e32 v45, 0, v41, vcc
	v_cmp_le_i32_e32 vcc, v53, v35
	v_lshrrev_b32_e32 v41, 16, v41
	s_nop 0
	v_cndmask_b32_e32 v41, 0, v41, vcc
	v_perm_b32 v45, v41, v45, s10
	v_add_u32_e32 v41, 0xfffffd80, v37
	ds_read_b64_tr_b16 v[46:47], v41
	v_subrev_u32_e32 v41, 64, v37
	ds_read_b64_tr_b16 v[48:49], v41
	v_add_u32_e32 v41, 0xfffffdc0, v37
	s_waitcnt lgkmcnt(0)
	v_mfma_f32_32x32x16_f16 v[18:33], v[46:49], v[42:45], v[18:33]
	ds_read_b64_tr_b16 v[46:47], v41
	ds_read_b64_tr_b16 v[48:49], v37
	v_cmp_eq_u32_e32 vcc, 0, v34
	v_add_u32_e32 v37, 0x900, v37
	s_or_b64 s[2:3], vcc, s[2:3]
	s_waitcnt lgkmcnt(0)
	v_mfma_f32_32x32x16_f16 v[2:17], v[46:49], v[42:45], v[2:17]
	s_andn2_b64 exec, exec, s[2:3]
	s_cbranch_execz .Lsg_ksdone
; #define MFMA(a, b, c) __builtin_amdgcn_mfma_f32_32x32x16_f16(__builtin_bit_cast(h16x8, (a)), __builtin_bit_cast(h16x8, (b)), (c), 0, 0, 0)
; DI unsigned pk2(float a, float b) { f2_t v = {a, b}; bf2_t r = __builtin_convertvector(v, bf2_t); return __builtin_bit_cast(unsigned, r); }
; DI void sg_item(const Params& p, int l, int item, char* lds, int dry) {
;     ...
;   const int nks = 2 * (w + 1);
;   for (int ks = 0; ks < nks; ++ks) {
;     const int s0 = ks * 16 + 8 * h;
;     const float4 w0 = *(const float4*)(wr + s0);
;     const float4 w1 = *(const float4*)(wr + s0 + 4);
;     float wv[8] = {w0.x, w0.y, w0.z, w0.w, w1.x, w1.y, w1.z, w1.w};
; #pragma unroll
;     for (int j = 0; j < 8; ++j) wv[j] = (s0 + j <= t) ? wv[j] : 0.f;
;     const uint4 uu = make_uint4(pk2(wv[0], wv[1]), pk2(wv[2], wv[3]), pk2(wv[4], wv[5]), pk2(wv[6], wv[7]));
;     const bf16x8 bfr = __builtin_bit_cast(bf16x8, uu);
; #pragma unroll
;     for (int db = 0; db < 2; ++db) {
;       const u16* vp = vn + (ks * 16 + 8 * h + q4) * 72 + db * 32 + 16 * blk + 4 * p4;
;       const s16x4 lo = __builtin_amdgcn_ds_read_tr16_b64_v4i16((__attribute__((address_space(3))) s16x4*)(vp));
;       const s16x4 hi = __builtin_amdgcn_ds_read_tr16_b64_v4i16((__attribute__((address_space(3))) s16x4*)(vp + 4 * 72));
;       const bf16x8 afr = __builtin_shufflevector(lo, hi, 0, 1, 2, 3, 4, 5, 6, 7);
;       acc[db] = MFMA(afr, bfr, acc[db]);
;     }
;   }
.Lsg_ks3:
	v_cmp_gt_i32_e32 vcc, v36, v40
	v_or_b32_e32 v50, 2, v40
	v_or_b32_e32 v52, 4, v40
	v_or_b32_e32 v51, 5, v40
	v_or_b32_e32 v54, 6, v40
	v_or_b32_e32 v53, 7, v40
	v_add_u32_e32 v34, -1, v34
	v_lshl_add_u64 v[38:39], v[38:39], 0, 64
	s_waitcnt vmcnt(9)
	v_cndmask_b32_e32 v41, 0, v121, vcc
	v_cmp_le_i32_e32 vcc, v40, v36
	v_or_b32_e32 v43, 3, v40
	v_add_u32_e32 v40, 16, v40
	v_cndmask_b32_e32 v42, 0, v120, vcc
	v_cvt_pk_f16_f32 v42, v42, v41
	v_cvt_pk_f16_f32 v41, v122, v123
	v_cmp_le_i32_e32 vcc, v50, v36
	s_nop 1
	v_cndmask_b32_e32 v44, 0, v41, vcc
	v_cmp_le_i32_e32 vcc, v43, v35
	v_lshrrev_b32_e32 v41, 16, v41
	s_nop 0
	v_cndmask_b32_e32 v41, 0, v41, vcc
	v_perm_b32 v43, v41, v44, s10
	s_waitcnt vmcnt(8)
	v_cvt_pk_f16_f32 v41, v124, v125
	v_cmp_le_i32_e32 vcc, v52, v36
	s_nop 1
	v_cndmask_b32_e32 v44, 0, v41, vcc
	v_cmp_le_i32_e32 vcc, v51, v35
	v_lshrrev_b32_e32 v41, 16, v41
	s_nop 0
	v_cndmask_b32_e32 v41, 0, v41, vcc
	v_perm_b32 v44, v41, v44, s10
	v_cvt_pk_f16_f32 v41, v126, v127
	v_cmp_le_i32_e32 vcc, v54, v36
	s_nop 1
	v_cndmask_b32_e32 v45, 0, v41, vcc
	v_cmp_le_i32_e32 vcc, v53, v35
	v_lshrrev_b32_e32 v41, 16, v41
	s_nop 0
	v_cndmask_b32_e32 v41, 0, v41, vcc
	v_perm_b32 v45, v41, v45, s10
	v_add_u32_e32 v41, 0xfffffd80, v37
	ds_read_b64_tr_b16 v[46:47], v41
	v_subrev_u32_e32 v41, 64, v37
	ds_read_b64_tr_b16 v[48:49], v41
	v_add_u32_e32 v41, 0xfffffdc0, v37
	s_waitcnt lgkmcnt(0)
	v_mfma_f32_32x32x16_f16 v[18:33], v[46:49], v[42:45], v[18:33]
	ds_read_b64_tr_b16 v[46:47], v41
	ds_read_b64_tr_b16 v[48:49], v37
	v_cmp_eq_u32_e32 vcc, 0, v34
	v_add_u32_e32 v37, 0x900, v37
	s_or_b64 s[2:3], vcc, s[2:3]
	s_waitcnt lgkmcnt(0)
	v_mfma_f32_32x32x16_f16 v[2:17], v[46:49], v[42:45], v[2:17]
	s_andn2_b64 exec, exec, s[2:3]
	s_cbranch_execz .Lsg_ksdone
.Lsg_ks4:
	v_cmp_gt_i32_e32 vcc, v36, v40
	v_or_b32_e32 v50, 2, v40
	v_or_b32_e32 v52, 4, v40
	v_or_b32_e32 v51, 5, v40
	v_or_b32_e32 v54, 6, v40
	v_or_b32_e32 v53, 7, v40
	v_add_u32_e32 v34, -1, v34
	v_lshl_add_u64 v[38:39], v[38:39], 0, 64
	s_waitcnt vmcnt(7)
	v_cndmask_b32_e32 v41, 0, v129, vcc
	v_cmp_le_i32_e32 vcc, v40, v36
	v_or_b32_e32 v43, 3, v40
	v_add_u32_e32 v40, 16, v40
	v_cndmask_b32_e32 v42, 0, v128, vcc
	v_cvt_pk_f16_f32 v42, v42, v41
	v_cvt_pk_f16_f32 v41, v130, v131
	v_cmp_le_i32_e32 vcc, v50, v36
	s_nop 1
	v_cndmask_b32_e32 v44, 0, v41, vcc
	v_cmp_le_i32_e32 vcc, v43, v35
	v_lshrrev_b32_e32 v41, 16, v41
	s_nop 0
	v_cndmask_b32_e32 v41, 0, v41, vcc
	v_perm_b32 v43, v41, v44, s10
	s_waitcnt vmcnt(6)
	v_cvt_pk_f16_f32 v41, v132, v133
	v_cmp_le_i32_e32 vcc, v52, v36
	s_nop 1
	v_cndmask_b32_e32 v44, 0, v41, vcc
	v_cmp_le_i32_e32 vcc, v51, v35
	v_lshrrev_b32_e32 v41, 16, v41
	s_nop 0
	v_cndmask_b32_e32 v41, 0, v41, vcc
	v_perm_b32 v44, v41, v44, s10
	v_cvt_pk_f16_f32 v41, v134, v135
	v_cmp_le_i32_e32 vcc, v54, v36
	s_nop 1
	v_cndmask_b32_e32 v45, 0, v41, vcc
	v_cmp_le_i32_e32 vcc, v53, v35
	v_lshrrev_b32_e32 v41, 16, v41
	s_nop 0
	v_cndmask_b32_e32 v41, 0, v41, vcc
	v_perm_b32 v45, v41, v45, s10
	v_add_u32_e32 v41, 0xfffffd80, v37
	ds_read_b64_tr_b16 v[46:47], v41
	v_subrev_u32_e32 v41, 64, v37
	ds_read_b64_tr_b16 v[48:49], v41
	v_add_u32_e32 v41, 0xfffffdc0, v37
	s_waitcnt lgkmcnt(0)
	v_mfma_f32_32x32x16_f16 v[18:33], v[46:49], v[42:45], v[18:33]
	ds_read_b64_tr_b16 v[46:47], v41
	ds_read_b64_tr_b16 v[48:49], v37
	v_cmp_eq_u32_e32 vcc, 0, v34
	v_add_u32_e32 v37, 0x900, v37
	s_or_b64 s[2:3], vcc, s[2:3]
	s_waitcnt lgkmcnt(0)
	v_mfma_f32_32x32x16_f16 v[2:17], v[46:49], v[42:45], v[2:17]
	s_andn2_b64 exec, exec, s[2:3]
	s_cbranch_execz .Lsg_ksdone
.Lsg_ks5:
	v_cmp_gt_i32_e32 vcc, v36, v40
	v_or_b32_e32 v50, 2, v40
	v_or_b32_e32 v52, 4, v40
	v_or_b32_e32 v51, 5, v40
	v_or_b32_e32 v54, 6, v40
	v_or_b32_e32 v53, 7, v40
	v_add_u32_e32 v34, -1, v34
	v_lshl_add_u64 v[38:39], v[38:39], 0, 64
	s_waitcnt vmcnt(5)
	v_cndmask_b32_e32 v41, 0, v137, vcc
	v_cmp_le_i32_e32 vcc, v40, v36
	v_or_b32_e32 v43, 3, v40
	v_add_u32_e32 v40, 16, v40
	v_cndmask_b32_e32 v42, 0, v136, vcc
	v_cvt_pk_f16_f32 v42, v42, v41
	v_cvt_pk_f16_f32 v41, v138, v139
	v_cmp_le_i32_e32 vcc, v50, v36
	s_nop 1
	v_cndmask_b32_e32 v44, 0, v41, vcc
	v_cmp_le_i32_e32 vcc, v43, v35
	v_lshrrev_b32_e32 v41, 16, v41
	s_nop 0
	v_cndmask_b32_e32 v41, 0, v41, vcc
	v_perm_b32 v43, v41, v44, s10
	s_waitcnt vmcnt(4)
	v_cvt_pk_f16_f32 v41, v140, v141
	v_cmp_le_i32_e32 vcc, v52, v36
	s_nop 1
	v_cndmask_b32_e32 v44, 0, v41, vcc
	v_cmp_le_i32_e32 vcc, v51, v35
	v_lshrrev_b32_e32 v41, 16, v41
	s_nop 0
	v_cndmask_b32_e32 v41, 0, v41, vcc
	v_perm_b32 v44, v41, v44, s10
	v_cvt_pk_f16_f32 v41, v142, v143
	v_cmp_le_i32_e32 vcc, v54, v36
	s_nop 1
	v_cndmask_b32_e32 v45, 0, v41, vcc
	v_cmp_le_i32_e32 vcc, v53, v35
	v_lshrrev_b32_e32 v41, 16, v41
	s_nop 0
	v_cndmask_b32_e32 v41, 0, v41, vcc
	v_perm_b32 v45, v41, v45, s10
	v_add_u32_e32 v41, 0xfffffd80, v37
	ds_read_b64_tr_b16 v[46:47], v41
	v_subrev_u32_e32 v41, 64, v37
	ds_read_b64_tr_b16 v[48:49], v41
	v_add_u32_e32 v41, 0xfffffdc0, v37
	s_waitcnt lgkmcnt(0)
	v_mfma_f32_32x32x16_f16 v[18:33], v[46:49], v[42:45], v[18:33]
	ds_read_b64_tr_b16 v[46:47], v41
	ds_read_b64_tr_b16 v[48:49], v37
	v_cmp_eq_u32_e32 vcc, 0, v34
	v_add_u32_e32 v37, 0x900, v37
	s_or_b64 s[2:3], vcc, s[2:3]
	s_waitcnt lgkmcnt(0)
	v_mfma_f32_32x32x16_f16 v[2:17], v[46:49], v[42:45], v[2:17]
	s_andn2_b64 exec, exec, s[2:3]
	s_cbranch_execz .Lsg_ksdone
; #define MFMA(a, b, c) __builtin_amdgcn_mfma_f32_32x32x16_f16(__builtin_bit_cast(h16x8, (a)), __builtin_bit_cast(h16x8, (b)), (c), 0, 0, 0)
; DI unsigned pk2(float a, float b) { f2_t v = {a, b}; bf2_t r = __builtin_convertvector(v, bf2_t); return __builtin_bit_cast(unsigned, r); }
; DI float bflo(unsigned u) { return (float)__builtin_bit_cast(bf2_t, u)[0]; }
; DI float bfhi(unsigned u) { return (float)__builtin_bit_cast(bf2_t, u)[1]; }
; DI float siluf_(float x) { return x / (1.f + __expf(-x)); }
; DI float geluf_(float x) { return 0.5f * x * (1.f + erff(x * 0.70710678118654752f)); }
; DI void sg_item(const Params& p, int l, int item, char* lds, int dry) {
;     ...
;   const int nks = 2 * (w + 1);
;   for (int ks = 0; ks < nks; ++ks) {
;     const int s0 = ks * 16 + 8 * h;
;     const float4 w0 = *(const float4*)(wr + s0);
;     const float4 w1 = *(const float4*)(wr + s0 + 4);
;     float wv[8] = {w0.x, w0.y, w0.z, w0.w, w1.x, w1.y, w1.z, w1.w};
; #pragma unroll
;     for (int j = 0; j < 8; ++j) wv[j] = (s0 + j <= t) ? wv[j] : 0.f;
;     const uint4 uu = make_uint4(pk2(wv[0], wv[1]), pk2(wv[2], wv[3]), pk2(wv[4], wv[5]), pk2(wv[6], wv[7]));
;     const bf16x8 bfr = __builtin_bit_cast(bf16x8, uu);
; #pragma unroll
;     for (int db = 0; db < 2; ++db) {
;       const u16* vp = vn + (ks * 16 + 8 * h + q4) * 72 + db * 32 + 16 * blk + 4 * p4;
;       const s16x4 lo = __builtin_amdgcn_ds_read_tr16_b64_v4i16((__attribute__((address_space(3))) s16x4*)(vp));
;       const s16x4 hi = __builtin_amdgcn_ds_read_tr16_b64_v4i16((__attribute__((address_space(3))) s16x4*)(vp + 4 * 72));
;       const bf16x8 afr = __builtin_shufflevector(lo, hi, 0, 1, 2, 3, 4, 5, 6, 7);
;       acc[db] = MFMA(afr, bfr, acc[db]);
;     }
;   }
;   const float bsv = p.b_spatial[(l * 8 + g) * 128 + t];
;   u16* zr = p.z + (tokbase + t) * ZS;
; #pragma unroll
;   for (int db = 0; db < 2; ++db)
; #pragma unroll
;     for (int a4 = 0; a4 < 4; ++a4) {
;       const int d = db * 32 + 8 * a4 + 4 * h;
;       const uint2 uv = *(const uint2*)(zr + UD + g * 64 + d);
;       uint2* gp = (uint2*)(zr + GD + g * 64 + d);
;       const uint2 gv = *gp;
;       uint2 o;
;       o.x = pk2(geluf_(bflo(uv.x)) * (acc[db][4 * a4] + bsv) * siluf_(bflo(gv.x)),
;                 geluf_(bfhi(uv.x)) * (acc[db][4 * a4 + 1] + bsv) * siluf_(bfhi(gv.x)));
.Lsg_ks6:
	v_cmp_gt_i32_e32 vcc, v36, v40
	v_or_b32_e32 v50, 2, v40
	v_or_b32_e32 v52, 4, v40
	v_or_b32_e32 v51, 5, v40
	v_or_b32_e32 v54, 6, v40
	v_or_b32_e32 v53, 7, v40
	v_add_u32_e32 v34, -1, v34
	v_lshl_add_u64 v[38:39], v[38:39], 0, 64
	s_waitcnt vmcnt(3)
	v_cndmask_b32_e32 v41, 0, v145, vcc
	v_cmp_le_i32_e32 vcc, v40, v36
	v_or_b32_e32 v43, 3, v40
	v_add_u32_e32 v40, 16, v40
	v_cndmask_b32_e32 v42, 0, v144, vcc
	v_cvt_pk_f16_f32 v42, v42, v41
	v_cvt_pk_f16_f32 v41, v146, v147
	v_cmp_le_i32_e32 vcc, v50, v36
	s_nop 1
	v_cndmask_b32_e32 v44, 0, v41, vcc
	v_cmp_le_i32_e32 vcc, v43, v35
	v_lshrrev_b32_e32 v41, 16, v41
	s_nop 0
	v_cndmask_b32_e32 v41, 0, v41, vcc
	v_perm_b32 v43, v41, v44, s10
	s_waitcnt vmcnt(2)
	v_cvt_pk_f16_f32 v41, v148, v149
	v_cmp_le_i32_e32 vcc, v52, v36
	s_nop 1
	v_cndmask_b32_e32 v44, 0, v41, vcc
	v_cmp_le_i32_e32 vcc, v51, v35
	v_lshrrev_b32_e32 v41, 16, v41
	s_nop 0
	v_cndmask_b32_e32 v41, 0, v41, vcc
	v_perm_b32 v44, v41, v44, s10
	v_cvt_pk_f16_f32 v41, v150, v151
	v_cmp_le_i32_e32 vcc, v54, v36
	s_nop 1
	v_cndmask_b32_e32 v45, 0, v41, vcc
	v_cmp_le_i32_e32 vcc, v53, v35
	v_lshrrev_b32_e32 v41, 16, v41
	s_nop 0
	v_cndmask_b32_e32 v41, 0, v41, vcc
	v_perm_b32 v45, v41, v45, s10
	v_add_u32_e32 v41, 0xfffffd80, v37
	ds_read_b64_tr_b16 v[46:47], v41
	v_subrev_u32_e32 v41, 64, v37
	ds_read_b64_tr_b16 v[48:49], v41
	v_add_u32_e32 v41, 0xfffffdc0, v37
	s_waitcnt lgkmcnt(0)
	v_mfma_f32_32x32x16_f16 v[18:33], v[46:49], v[42:45], v[18:33]
	ds_read_b64_tr_b16 v[46:47], v41
	ds_read_b64_tr_b16 v[48:49], v37
	v_cmp_eq_u32_e32 vcc, 0, v34
	v_add_u32_e32 v37, 0x900, v37
	s_or_b64 s[2:3], vcc, s[2:3]
	s_waitcnt lgkmcnt(0)
	v_mfma_f32_32x32x16_f16 v[2:17], v[46:49], v[42:45], v[2:17]
	s_andn2_b64 exec, exec, s[2:3]
	s_cbranch_execz .Lsg_ksdone
.Lsg_ks7:
	v_cmp_gt_i32_e32 vcc, v36, v40
	v_or_b32_e32 v50, 2, v40
	v_or_b32_e32 v52, 4, v40
	v_or_b32_e32 v51, 5, v40
	v_or_b32_e32 v54, 6, v40
	v_or_b32_e32 v53, 7, v40
	v_add_u32_e32 v34, -1, v34
	v_lshl_add_u64 v[38:39], v[38:39], 0, 64
	s_waitcnt vmcnt(1)
	v_cndmask_b32_e32 v41, 0, v153, vcc
	v_cmp_le_i32_e32 vcc, v40, v36
	v_or_b32_e32 v43, 3, v40
	v_add_u32_e32 v40, 16, v40
	v_cndmask_b32_e32 v42, 0, v152, vcc
	v_cvt_pk_f16_f32 v42, v42, v41
	v_cvt_pk_f16_f32 v41, v154, v155
	v_cmp_le_i32_e32 vcc, v50, v36
	s_nop 1
	v_cndmask_b32_e32 v44, 0, v41, vcc
	v_cmp_le_i32_e32 vcc, v43, v35
	v_lshrrev_b32_e32 v41, 16, v41
	s_nop 0
	v_cndmask_b32_e32 v41, 0, v41, vcc
	v_perm_b32 v43, v41, v44, s10
	s_waitcnt vmcnt(0)
	v_cvt_pk_f16_f32 v41, v156, v157
	v_cmp_le_i32_e32 vcc, v52, v36
	s_nop 1
	v_cndmask_b32_e32 v44, 0, v41, vcc
	v_cmp_le_i32_e32 vcc, v51, v35
	v_lshrrev_b32_e32 v41, 16, v41
	s_nop 0
	v_cndmask_b32_e32 v41, 0, v41, vcc
	v_perm_b32 v44, v41, v44, s10
	v_cvt_pk_f16_f32 v41, v158, v159
	v_cmp_le_i32_e32 vcc, v54, v36
	s_nop 1
	v_cndmask_b32_e32 v45, 0, v41, vcc
	v_cmp_le_i32_e32 vcc, v53, v35
	v_lshrrev_b32_e32 v41, 16, v41
	s_nop 0
	v_cndmask_b32_e32 v41, 0, v41, vcc
	v_perm_b32 v45, v41, v45, s10
	v_add_u32_e32 v41, 0xfffffd80, v37
	ds_read_b64_tr_b16 v[46:47], v41
	v_subrev_u32_e32 v41, 64, v37
	ds_read_b64_tr_b16 v[48:49], v41
	v_add_u32_e32 v41, 0xfffffdc0, v37
	s_waitcnt lgkmcnt(0)
	v_mfma_f32_32x32x16_f16 v[18:33], v[46:49], v[42:45], v[18:33]
	ds_read_b64_tr_b16 v[46:47], v41
	ds_read_b64_tr_b16 v[48:49], v37
	v_cmp_eq_u32_e32 vcc, 0, v34
	v_add_u32_e32 v37, 0x900, v37
	s_or_b64 s[2:3], vcc, s[2:3]
	s_waitcnt lgkmcnt(0)
	v_mfma_f32_32x32x16_f16 v[2:17], v[46:49], v[42:45], v[2:17]
	s_andn2_b64 exec, exec, s[2:3]
.Lsg_ksdone:
	s_or_b64 exec, exec, s[2:3]
.LBB0_784:
	s_or_b64 exec, exec, s[0:1]
	s_or_b32 s0, s9, s8
	v_add_u32_e32 v34, s0, v36
	v_readlane_b32 s80, v251, 18
	v_ashrrev_i32_e32 v35, 31, v34
	v_readlane_b32 s81, v251, 19
	v_readlane_b32 s82, v251, 20
	v_readlane_b32 s83, v251, 21
	v_readlane_b32 s84, v251, 22
	v_readlane_b32 s85, v251, 23
	v_readlane_b32 s86, v251, 24
	v_readlane_b32 s87, v251, 25
	v_readlane_b32 s88, v251, 26
	v_readlane_b32 s89, v251, 27
	v_readlane_b32 s90, v251, 28
	v_readlane_b32 s91, v251, 29
	v_readlane_b32 s92, v251, 30
	v_readlane_b32 s93, v251, 31
	v_readlane_b32 s94, v251, 32
	v_readlane_b32 s95, v251, 33
	v_lshl_add_u64 v[34:35], v[34:35], 2, s[92:93]
	v_readlane_b32 s80, v253, 12
	v_readlane_b32 s86, v253, 18
	v_readlane_b32 s87, v253, 19
	global_load_dword v34, v[34:35], off
	v_add_u32_e32 v35, s7, v36
	v_mov_b64_e32 v[36:37], s[86:87]
	v_mad_i64_i32 v[36:37], s[0:1], v35, s75, v[36:37]
	v_lshl_add_u64 v[36:37], v[36:37], 0, s[18:19]
	v_lshl_add_u64 v[36:37], v[36:37], 0, v[0:1]
	v_add_co_u32_e32 v40, vcc, 0x2000, v36
	v_readlane_b32 s81, v253, 13
	s_nop 0
	v_addc_co_u32_e32 v41, vcc, 0, v37, vcc
	global_load_dwordx2 v[38:39], v[40:41], off offset:1536
	s_nop 0
	global_load_dwordx2 v[40:41], v[40:41], off offset:3584
	v_readlane_b32 s82, v253, 14
	v_readlane_b32 s83, v253, 15
	v_readlane_b32 s84, v253, 16
	v_readlane_b32 s85, v253, 17
	v_readlane_b32 s88, v253, 20
	v_readlane_b32 s89, v253, 21
	v_readlane_b32 s90, v253, 22
	v_readlane_b32 s91, v253, 23
	v_readlane_b32 s92, v253, 24
	v_readlane_b32 s93, v253, 25
	v_readlane_b32 s94, v253, 26
	v_readlane_b32 s95, v253, 27
	s_waitcnt vmcnt(1)
	v_cvt_f32_f16_e32 v0, v38
	v_mul_f32_e32 v35, 0x3f3504f3, v0
	v_cmp_nlt_f32_e64 s[0:1], |v35|, 1.0
	s_and_saveexec_b64 s[2:3], s[0:1]
	s_xor_b64 s[0:1], exec, s[2:3]
	s_cbranch_execz .LBB0_786
	v_fma_f32 v42, |v35|, s77, v224
	s_mov_b32 s2, 0x3b7cd369
	v_fma_f32 v42, |v35|, v42, s2
	s_mov_b32 s2, 0xbcc618b2
	v_fma_f32 v42, |v35|, v42, s2
	s_mov_b32 s2, 0x3dda74e4
	v_fma_f32 v42, |v35|, v42, s2
	s_mov_b32 s2, 0x3f228afd
	v_fma_f32 v42, |v35|, v42, s2
	s_mov_b32 s2, 0x3e03c728
	v_fma_f32 v42, |v35|, v42, s2
	v_fma_f32 v42, |v35|, v42, |v35|
	v_mul_f32_e32 v43, 0xbfb8aa3b, v42
	s_mov_b32 s2, 0xbfb8aa3b
	v_fma_f32 v44, v42, s2, -v43
	v_rndne_f32_e32 v45, v43
	v_fmac_f32_e32 v44, 0xb2a5705f, v42
	v_sub_f32_e32 v43, v43, v45
	v_add_f32_e32 v43, v43, v44
	v_cvt_i32_f32_e32 v44, v45
	v_exp_f32_e32 v43, v43
	s_mov_b32 s2, 0x42ce8ed0
	v_cmp_nlt_f32_e32 vcc, s2, v42
	s_mov_b32 s2, 0xc2b17218
	v_ldexp_f32 v43, v43, v44
	v_cndmask_b32_e32 v43, 0, v43, vcc
	v_cmp_ngt_f32_e32 vcc, s2, v42
	s_nop 1
	v_cndmask_b32_e32 v42, v225, v43, vcc
	v_sub_f32_e32 v44, 1.0, v42
